# grid barrier: two staggered polls of the arrival counter in flight per workgroup
# baseline (speedup 1.0000x reference)
.LBB0_188:
	s_or_b64 exec, exec, s[10:11]
	v_cvt_f32_u32_e32 v7, v4
	s_waitcnt vmcnt(0)
	v_readfirstlane_b32 s10, v5
	v_sub_u32_e32 v5, 0, v4
	v_rcp_iflag_f32_e32 v7, v7
	v_add_u32_e32 v8, s10, v1
	v_mul_f32_e32 v7, 0x4f7ffffe, v7
	v_cvt_u32_f32_e32 v7, v7
	v_mul_lo_u32 v1, v5, v7
	v_mul_hi_u32 v1, v7, v1
	v_add_u32_e32 v1, v7, v1
	v_mul_hi_u32 v1, v8, v1
	v_mul_lo_u32 v5, v1, v4
	v_sub_u32_e32 v5, v8, v5
	v_add_u32_e32 v7, 1, v1
	v_cmp_ge_u32_e32 vcc, v5, v4
	s_nop 1
	v_cndmask_b32_e32 v1, v1, v7, vcc
	v_sub_u32_e32 v7, v5, v4
	v_cndmask_b32_e32 v5, v5, v7, vcc
	v_add_u32_e32 v7, 1, v1
	v_cmp_ge_u32_e32 vcc, v5, v4
	v_add_u32_e32 v5, 1, v8
	s_nop 0
	v_cndmask_b32_e32 v1, v1, v7, vcc
	v_mul_lo_u32 v7, v4, v1
	v_add_u32_e32 v4, v7, v4
	v_cmp_ne_u32_e32 vcc, v5, v4
	buffer_inv sc1
	v_mov_b32_e32 v4, 0
	v_add_u32_e32 v8, 1, v1
	v_readlane_b32 s12, v252, 39
	v_readlane_b32 s13, v252, 40
	s_waitcnt lgkmcnt(0)
	v_mul_lo_u32 v7, v8, v2
	v_mov_b32_e32 v5, 1
	s_mov_b32 s25, 0
	s_nop 4
	s_cbranch_vccnz .Lxb_poll_1
	buffer_wbl2 sc1
	s_waitcnt vmcnt(0)
	global_atomic_add v3, v5, s[12:13]
.Lxb_poll_1:
	global_load_dword v2, v3, s[12:13] sc1
	s_sleep 16
	global_load_dword v4, v3, s[12:13] sc1
.Lxb_loop_1:
	s_waitcnt vmcnt(1)
	v_cmp_ge_u32_e32 vcc, v2, v7
	s_cbranch_vccnz .Lxb_done_1
	global_load_dword v2, v3, s[12:13] sc1
	s_waitcnt vmcnt(1)
	v_cmp_ge_u32_e32 vcc, v4, v7
	s_cbranch_vccnz .Lxb_done_1
	s_add_i32 s25, s25, 1
	s_and_b32 s20, s25, 0xff
	s_cmp_lg_u32 s20, 0
	s_cbranch_scc0 .Lxb_tmo_1
	global_load_dword v4, v3, s[12:13] sc1
	s_branch .Lxb_loop_1
.Lxb_tmo_1:
	s_waitcnt vmcnt(0)
	global_load_dword v4, v3, s[88:89] sc1
	s_waitcnt vmcnt(0)
	v_cmp_ne_u32_e32 vcc, 0, v4
	s_cbranch_vccnz .Lxb_done_1
	s_cmp_lt_u32 s25, 0x20001
	s_cbranch_scc0 .Lxb_tmoadd_1
	global_load_dword v4, v3, s[12:13] sc1
	s_branch .Lxb_loop_1
.Lxb_tmoadd_1:
	global_atomic_add v3, v5, s[88:89]

.LBB0_296:
	s_or_b64 exec, exec, s[12:13]
	v_cvt_f32_u32_e32 v7, v4
	s_waitcnt vmcnt(0)
	v_readfirstlane_b32 s12, v5
	v_sub_u32_e32 v5, 0, v4
	v_rcp_iflag_f32_e32 v7, v7
	v_add_u32_e32 v8, s12, v1
	v_mul_f32_e32 v7, 0x4f7ffffe, v7
	v_cvt_u32_f32_e32 v7, v7
	v_mul_lo_u32 v1, v5, v7
	v_mul_hi_u32 v1, v7, v1
	v_add_u32_e32 v1, v7, v1
	v_mul_hi_u32 v1, v8, v1
	v_mul_lo_u32 v5, v1, v4
	v_sub_u32_e32 v5, v8, v5
	v_add_u32_e32 v7, 1, v1
	v_cmp_ge_u32_e32 vcc, v5, v4
	s_nop 1
	v_cndmask_b32_e32 v1, v1, v7, vcc
	v_sub_u32_e32 v7, v5, v4
	v_cndmask_b32_e32 v5, v5, v7, vcc
	v_add_u32_e32 v7, 1, v1
	v_cmp_ge_u32_e32 vcc, v5, v4
	v_add_u32_e32 v5, 1, v8
	s_nop 0
	v_cndmask_b32_e32 v1, v1, v7, vcc
	v_mul_lo_u32 v7, v4, v1
	v_add_u32_e32 v4, v7, v4
	v_cmp_ne_u32_e32 vcc, v5, v4
	buffer_inv sc1
	v_mov_b32_e32 v4, 0
	v_add_u32_e32 v8, 1, v1
	v_readlane_b32 s14, v252, 39
	v_readlane_b32 s15, v252, 40
	s_waitcnt lgkmcnt(0)
	v_mul_lo_u32 v7, v8, v2
	v_mov_b32_e32 v5, 1
	s_mov_b32 s26, 0
	s_nop 4
	s_cbranch_vccnz .Lxb_poll_2
	buffer_wbl2 sc1
	s_waitcnt vmcnt(0)
	global_atomic_add v3, v5, s[14:15]
.Lxb_poll_2:
	global_load_dword v2, v3, s[14:15] sc1
	s_sleep 16
	global_load_dword v4, v3, s[14:15] sc1
.Lxb_loop_2:
	s_waitcnt vmcnt(1)
	v_cmp_ge_u32_e32 vcc, v2, v7
	s_cbranch_vccnz .Lxb_done_2
	global_load_dword v2, v3, s[14:15] sc1
	s_waitcnt vmcnt(1)
	v_cmp_ge_u32_e32 vcc, v4, v7
	s_cbranch_vccnz .Lxb_done_2
	s_add_i32 s26, s26, 1
	s_and_b32 s22, s26, 0xff
	s_cmp_lg_u32 s22, 0
	s_cbranch_scc0 .Lxb_tmo_2
	global_load_dword v4, v3, s[14:15] sc1
	s_branch .Lxb_loop_2
.Lxb_tmo_2:
	s_waitcnt vmcnt(0)
	global_load_dword v4, v3, s[88:89] sc1
	s_waitcnt vmcnt(0)
	v_cmp_ne_u32_e32 vcc, 0, v4
	s_cbranch_vccnz .Lxb_done_2
	s_cmp_lt_u32 s26, 0x20001
	s_cbranch_scc0 .Lxb_tmoadd_2
	global_load_dword v4, v3, s[14:15] sc1
	s_branch .Lxb_loop_2

.LBB0_940:
	s_or_b64 exec, exec, s[8:9]
	v_cvt_f32_u32_e32 v7, v4
	s_waitcnt vmcnt(0)
	v_readfirstlane_b32 s8, v5
	v_sub_u32_e32 v5, 0, v4
	v_rcp_iflag_f32_e32 v7, v7
	v_add_u32_e32 v8, s8, v1
	v_mul_f32_e32 v7, 0x4f7ffffe, v7
	v_cvt_u32_f32_e32 v7, v7
	v_mul_lo_u32 v1, v5, v7
	v_mul_hi_u32 v1, v7, v1
	v_add_u32_e32 v1, v7, v1
	v_mul_hi_u32 v1, v8, v1
	v_mul_lo_u32 v5, v1, v4
	v_sub_u32_e32 v5, v8, v5
	v_add_u32_e32 v7, 1, v1
	v_cmp_ge_u32_e32 vcc, v5, v4
	s_nop 1
	v_cndmask_b32_e32 v1, v1, v7, vcc
	v_sub_u32_e32 v7, v5, v4
	v_cndmask_b32_e32 v5, v5, v7, vcc
	v_add_u32_e32 v7, 1, v1
	v_cmp_ge_u32_e32 vcc, v5, v4
	v_add_u32_e32 v5, 1, v8
	s_nop 0
	v_cndmask_b32_e32 v1, v1, v7, vcc
	v_mul_lo_u32 v7, v4, v1
	v_add_u32_e32 v4, v7, v4
	v_cmp_ne_u32_e32 vcc, v5, v4
	buffer_inv sc1
	v_mov_b32_e32 v4, 0
	v_add_u32_e32 v8, 1, v1
	v_readlane_b32 s10, v252, 39
	v_readlane_b32 s11, v252, 40
	s_waitcnt lgkmcnt(0)
	v_mul_lo_u32 v7, v8, v2
	v_mov_b32_e32 v5, 1
	s_mov_b32 s22, 0
	s_nop 4
	s_cbranch_vccnz .Lxb_poll_6
	buffer_wbl2 sc1
	s_waitcnt vmcnt(0)
	global_atomic_add v3, v5, s[10:11]
.Lxb_poll_6:
	global_load_dword v2, v3, s[10:11] sc1
	s_sleep 16
	global_load_dword v4, v3, s[10:11] sc1
.Lxb_loop_6:
	s_waitcnt vmcnt(1)
	v_cmp_ge_u32_e32 vcc, v2, v7
	s_cbranch_vccnz .Lxb_done_6
	global_load_dword v2, v3, s[10:11] sc1
	s_waitcnt vmcnt(1)
	v_cmp_ge_u32_e32 vcc, v4, v7
	s_cbranch_vccnz .Lxb_done_6
	s_add_i32 s22, s22, 1
	s_and_b32 s18, s22, 0xff
	s_cmp_lg_u32 s18, 0
	s_cbranch_scc0 .Lxb_tmo_6
	global_load_dword v4, v3, s[10:11] sc1
	s_branch .Lxb_loop_6
.Lxb_tmo_6:
	s_waitcnt vmcnt(0)
	global_load_dword v4, v3, s[88:89] sc1
	s_waitcnt vmcnt(0)
	v_cmp_ne_u32_e32 vcc, 0, v4
	s_cbranch_vccnz .Lxb_done_6
	s_cmp_lt_u32 s22, 0x20001
	s_cbranch_scc0 .Lxb_tmoadd_6
	global_load_dword v4, v3, s[10:11] sc1
	s_branch .Lxb_loop_6

.LBB0_1508:
	s_or_b64 exec, exec, s[10:11]
	v_cvt_f32_u32_e32 v7, v4
	s_waitcnt vmcnt(0)
	v_readfirstlane_b32 s10, v5
	v_sub_u32_e32 v5, 0, v4
	v_rcp_iflag_f32_e32 v7, v7
	v_add_u32_e32 v8, s10, v1
	v_mul_f32_e32 v7, 0x4f7ffffe, v7
	v_cvt_u32_f32_e32 v7, v7
	v_mul_lo_u32 v1, v5, v7
	v_mul_hi_u32 v1, v7, v1
	v_add_u32_e32 v1, v7, v1
	v_mul_hi_u32 v1, v8, v1
	v_mul_lo_u32 v5, v1, v4
	v_sub_u32_e32 v5, v8, v5
	v_add_u32_e32 v7, 1, v1
	v_cmp_ge_u32_e32 vcc, v5, v4
	s_nop 1
	v_cndmask_b32_e32 v1, v1, v7, vcc
	v_sub_u32_e32 v7, v5, v4
	v_cndmask_b32_e32 v5, v5, v7, vcc
	v_add_u32_e32 v7, 1, v1
	v_cmp_ge_u32_e32 vcc, v5, v4
	v_add_u32_e32 v5, 1, v8
	s_nop 0
	v_cndmask_b32_e32 v1, v1, v7, vcc
	v_mul_lo_u32 v7, v4, v1
	v_add_u32_e32 v4, v7, v4
	v_cmp_ne_u32_e32 vcc, v5, v4
	buffer_inv sc1
	v_mov_b32_e32 v4, 0
	v_add_u32_e32 v8, 1, v1
	v_readlane_b32 s12, v252, 39
	v_readlane_b32 s13, v252, 40
	s_waitcnt lgkmcnt(0)
	v_mul_lo_u32 v7, v8, v2
	v_mov_b32_e32 v5, 1
	s_mov_b32 s24, 0
	s_nop 4
	s_cbranch_vccnz .Lxb_poll_10
	buffer_wbl2 sc1
	s_waitcnt vmcnt(0)
	global_atomic_add v3, v5, s[12:13]

.Lxb_loop_10:
	s_waitcnt vmcnt(1)
	v_cmp_ge_u32_e32 vcc, v2, v7
	s_cbranch_vccnz .Lxb_done_10
	global_load_dword v2, v3, s[12:13] sc1
	s_waitcnt vmcnt(1)
	v_cmp_ge_u32_e32 vcc, v4, v7
	s_cbranch_vccnz .Lxb_done_10
	s_add_i32 s24, s24, 1
	s_and_b32 s20, s24, 0xff
	s_cmp_lg_u32 s20, 0
	s_cbranch_scc0 .Lxb_tmo_10
	global_load_dword v4, v3, s[12:13] sc1
	s_branch .Lxb_loop_10
.Lxb_tmo_10:
	s_waitcnt vmcnt(0)
	global_load_dword v4, v3, s[88:89] sc1
	s_waitcnt vmcnt(0)
	v_cmp_ne_u32_e32 vcc, 0, v4
	s_cbranch_vccnz .Lxb_done_10
	s_cmp_lt_u32 s24, 0x20001
	s_cbranch_scc0 .Lxb_tmoadd_10
	global_load_dword v4, v3, s[12:13] sc1
	s_branch .Lxb_loop_10
